# weight conversions WO,W5,W6 (both layers) and W1,W2 (layer 1) done by the scan helper waves (register/DPP transposer) while HBM is idle; tails keep W2,WIN L0 (ph1) and WIN L1 (ph10)
# speedup vs baseline: 1.0079x; 1.0079x over previous
.LBB0_76:
	s_mov_b32 s98, 0
	s_mov_b32 s17, 0x1
	s_cmp_eq_u32 s88, 0
	s_cbranch_scc1 .LBB0_81
	s_mov_b32 s17, 0
	s_mov_b32 s99, 0
	s_cmp_eq_u32 s88, 1
	s_cselect_b32 s17, 0x6, s17
	s_cselect_b32 s99, 0x96, s99
	s_cmp_eq_u32 s88, 10
	s_cselect_b32 s17, 0x100, s17
	s_cselect_b32 s99, 0x96, s99
	s_cmp_eq_u32 s17, 0
	s_cbranch_scc1 .LBB0_78
	s_cmp_lt_u32 s2, s99
	s_cbranch_scc0 .Lcv_idle

.LBB0_533:
	s_and_b64 vcc, exec, s[0:1]
	s_cbranch_vccz .LBB0_508
	v_mov_b32_e32 v57, v241
	s_ashr_i32 s48, s8, 5
	s_bfe_u32 s9, s8, 0x40001
	v_readfirstlane_b32 s0, v57
	s_and_b32 s10, s8, 1
	s_ashr_i32 s11, s0, 6
	s_ashr_i32 s49, s48, 31
	s_cmp_gt_i32 s11, 3
	s_mov_b64 s[0:1], -1
	s_cbranch_scc0 .LBB0_606
	s_waitcnt vmcnt(0)
	v_add_u32_e32 v198, 0xffffff00, v241
	v_lshrrev_b32_e32 v206, 3, v198
	v_and_b32_e32 v207, 7, v198
	s_lshl_b32 s0, s9, 6
	v_lshl_add_u32 v208, v207, 2, s0
	v_cmp_eq_u32_e64 s[38:39], 0, v207
	v_cmp_gt_u32_e64 s[28:29], 16, v206
	s_cmp_eq_u32 s10, 0
	s_cselect_b64 s[40:41], -1, 0
	s_nop 3
	s_and_b64 s[40:41], s[40:41], s[38:39]
	v_lshlrev_b32_e32 v199, 2, v208
	v_readlane_b32 s4, v255, 32
	v_readlane_b32 s5, v255, 33
	v_readlane_b32 s12, v255, 47
	v_readlane_b32 s13, v255, 48
	v_readlane_b32 s0, v255, 49
	v_readlane_b32 s1, v255, 50
	s_nop 4
	s_add_u32 s6, s4, 0x1000
	s_addc_u32 s7, s5, 0
	global_load_dwordx4 v[0:3], v199, s[4:5]
	global_load_dwordx4 v[4:7], v199, s[4:5] offset:128
	global_load_dwordx4 v[8:11], v199, s[6:7]
	global_load_dwordx4 v[12:15], v199, s[6:7] offset:128
	s_add_u32 s6, s4, 0x2000
	s_addc_u32 s7, s5, 0
	global_load_dwordx4 v[24:27], v199, s[12:13]
	global_load_dwordx4 v[28:31], v199, s[12:13] offset:128
	global_load_dwordx4 v[16:19], v199, s[6:7]
	global_load_dwordx4 v[20:23], v199, s[6:7] offset:128
	global_load_dwordx4 v[32:35], v199, s[0:1]
	global_load_dwordx4 v[36:39], v199, s[0:1] offset:128
	global_load_dwordx4 v[40:43], v199, s[64:65]
	global_load_dwordx4 v[44:47], v199, s[64:65] offset:128
	v_mov_b32_e32 v48, 0x3fb8aa3b
	v_mov_b32_e32 v49, 0x3fb8aa3b
	s_mul_i32 s0, s48, 0x810
	v_add_u32_e32 v209, s0, v206
	v_mov_b32_e32 v211, 0
	v_lshlrev_b32_e32 v210, 1, v208
	s_movk_i32 s14, 0x1a00
	v_mad_u64_u32 v[182:183], s[0:1], v209, s14, v[210:211]
	s_add_u32 s4, s86, 0x81a7000
	s_addc_u32 s5, s87, 0
	v_lshl_add_u64 v[182:183], v[182:183], 0, s[4:5]
	s_mov_b64 s[0:1], 0x1000
	v_lshl_add_u64 v[178:179], v[182:183], 0, s[0:1]
	v_lshl_add_u64 v[180:181], v[178:179], 0, s[0:1]
	v_lshl_add_u32 v198, v209, 11, v210
	v_mov_b32_e32 v210, v198
	s_add_u32 s4, s86, 0xeb48000
	s_addc_u32 s5, s87, 0
	v_lshl_add_u64 v[186:187], v[210:211], 0, s[4:5]
	s_add_u32 s4, s86, 0x10bc8000
	s_addc_u32 s5, s87, 0
	v_lshl_add_u64 v[188:189], v[210:211], 0, s[4:5]
	s_lshl_b32 s0, s9, 6
	s_lshl_b32 s1, s10, 5
	s_add_i32 s0, s0, s1
	v_lshl_add_u32 v198, v207, 2, s0
	v_lshlrev_b32_e32 v198, 1, v198
	v_lshl_add_u32 v210, v209, 11, v198
	s_add_u32 s4, s86, 0x5700000
	s_addc_u32 s5, s87, 0
	v_lshl_add_u64 v[190:191], v[210:211], 0, s[4:5]
	s_lshl_b32 s0, s9, 2
	v_lshl_add_u32 v210, v209, 6, s0
	s_add_u32 s4, s86, 0x7884000
	s_addc_u32 s5, s87, 0
	v_lshl_add_u64 v[192:193], v[210:211], 0, s[4:5]
	v_mul_u32_u24_e32 v194, 0x600, v206
	v_lshl_add_u32 v194, v207, 4, v194
	s_lshl_b32 s0, s10, 7
	v_mul_u32_u24_e32 v222, 0x600, v206
	v_lshl_add_u32 v222, v207, 4, v222
	v_add_u32_e32 v222, s0, v222
	v_lshlrev_b32_e32 v195, 7, v206
	v_lshl_add_u32 v195, v207, 4, v195
	v_add_u32_e32 v195, 0x18000, v195
	v_lshlrev_b32_e32 v196, 2, v206
	v_add_u32_e32 v196, 0x1a000, v196
	v_lshlrev_b32_e32 v197, 3, v206
	v_add_u32_e32 v197, 0x1a100, v197
	v_and_b32_e32 v231, 63, v241
	v_and_b32_e32 v240, 1, v231
	v_and_b32_e32 v233, 62, v231
	v_lshlrev_b32_e32 v233, 1, v233
	v_lshlrev_b32_e32 v250, 2, v231
	s_lshl_b32 s53, s8, 2
	s_add_i32 s53, s53, s11
	s_add_i32 s53, s53, -4
	s_mov_b32 s62, 0x55555555
	s_mov_b32 s63, 0x55555555
	s_mov_b32 s34, 0
	global_load_dwordx2 v[52:53], v[178:179], off
	global_load_dwordx2 v[54:55], v[178:179], off offset:64
	global_load_dwordx2 v[56:57], v[178:179], off offset:2048
	global_load_dwordx2 v[58:59], v[178:179], off offset:2112
	global_load_dwordx2 v[60:61], v[180:181], off
	global_load_dwordx2 v[62:63], v[180:181], off offset:64
	global_load_dwordx2 v[64:65], v[182:183], off offset:-2560
	global_load_dwordx2 v[66:67], v[182:183], off offset:-2496
	global_load_dwordx2 v[68:69], v[182:183], off offset:-512
	global_load_dwordx2 v[70:71], v[182:183], off offset:-448
	global_load_dwordx2 v[72:73], v[178:179], off offset:-2560
	global_load_dwordx2 v[74:75], v[178:179], off offset:-2496
	global_load_dwordx2 v[76:77], v[186:187], off
	global_load_dwordx2 v[78:79], v[186:187], off offset:64
	global_load_dwordx2 v[80:81], v[188:189], off
	global_load_dwordx2 v[82:83], v[188:189], off offset:64
	s_mov_b32 s13, 0
	s_waitcnt vmcnt(0)
	v_cmp_ne_u32_e64 s[6:7], 0, v206
	s_nop 3
	v_cndmask_b32_e64 v64, 0, v64, s[6:7]
	v_cndmask_b32_e64 v65, 0, v65, s[6:7]
	v_cndmask_b32_e64 v66, 0, v66, s[6:7]
	v_cndmask_b32_e64 v67, 0, v67, s[6:7]
	v_cndmask_b32_e64 v68, 0, v68, s[6:7]
	v_cndmask_b32_e64 v69, 0, v69, s[6:7]
	v_cndmask_b32_e64 v70, 0, v70, s[6:7]
	v_cndmask_b32_e64 v71, 0, v71, s[6:7]
	v_cndmask_b32_e64 v72, 0, v72, s[6:7]
	v_cndmask_b32_e64 v73, 0, v73, s[6:7]
	v_cndmask_b32_e64 v74, 0, v74, s[6:7]
	v_cndmask_b32_e64 v75, 0, v75, s[6:7]
	v_lshlrev_b32_e32 v84, 16, v52
	v_and_b32_e32 v85, 0xffff0000, v52
	v_lshlrev_b32_e32 v86, 16, v53
	v_and_b32_e32 v87, 0xffff0000, v53
	v_lshlrev_b32_e32 v88, 16, v54
	v_and_b32_e32 v89, 0xffff0000, v54
	v_lshlrev_b32_e32 v90, 16, v55
	v_and_b32_e32 v91, 0xffff0000, v55
	v_lshlrev_b32_e32 v124, 16, v64
	v_and_b32_e32 v125, 0xffff0000, v64
	v_lshlrev_b32_e32 v126, 16, v65
	v_and_b32_e32 v127, 0xffff0000, v65
	v_lshlrev_b32_e32 v128, 16, v66
	v_and_b32_e32 v129, 0xffff0000, v66
	v_lshlrev_b32_e32 v130, 16, v67
	v_and_b32_e32 v131, 0xffff0000, v67
	v_pk_add_f32 v[124:125], v[124:125], v[84:85] neg_lo:[0,1] neg_hi:[0,1]
	v_pk_add_f32 v[126:127], v[126:127], v[86:87] neg_lo:[0,1] neg_hi:[0,1]
	v_pk_add_f32 v[128:129], v[128:129], v[88:89] neg_lo:[0,1] neg_hi:[0,1]
	v_pk_add_f32 v[130:131], v[130:131], v[90:91] neg_lo:[0,1] neg_hi:[0,1]
	v_pk_fma_f32 v[84:85], v[0:1], v[124:125], v[84:85]
	v_pk_fma_f32 v[86:87], v[2:3], v[126:127], v[86:87]
	v_pk_fma_f32 v[88:89], v[4:5], v[128:129], v[88:89]
	v_pk_fma_f32 v[90:91], v[6:7], v[130:131], v[90:91]
	v_lshlrev_b32_e32 v92, 16, v56
	v_and_b32_e32 v93, 0xffff0000, v56
	v_lshlrev_b32_e32 v94, 16, v57
	v_and_b32_e32 v95, 0xffff0000, v57
	v_lshlrev_b32_e32 v96, 16, v58
	v_and_b32_e32 v97, 0xffff0000, v58
	v_lshlrev_b32_e32 v98, 16, v59
	v_and_b32_e32 v99, 0xffff0000, v59
	v_lshlrev_b32_e32 v124, 16, v68
	v_and_b32_e32 v125, 0xffff0000, v68
	v_lshlrev_b32_e32 v126, 16, v69
	v_and_b32_e32 v127, 0xffff0000, v69
	v_lshlrev_b32_e32 v128, 16, v70
	v_and_b32_e32 v129, 0xffff0000, v70
	v_lshlrev_b32_e32 v130, 16, v71
	v_and_b32_e32 v131, 0xffff0000, v71
	v_pk_add_f32 v[124:125], v[124:125], v[92:93] neg_lo:[0,1] neg_hi:[0,1]
	v_pk_add_f32 v[126:127], v[126:127], v[94:95] neg_lo:[0,1] neg_hi:[0,1]
	v_pk_add_f32 v[128:129], v[128:129], v[96:97] neg_lo:[0,1] neg_hi:[0,1]
	v_pk_add_f32 v[130:131], v[130:131], v[98:99] neg_lo:[0,1] neg_hi:[0,1]
	v_pk_fma_f32 v[92:93], v[8:9], v[124:125], v[92:93]
	v_pk_fma_f32 v[94:95], v[10:11], v[126:127], v[94:95]
	v_pk_fma_f32 v[96:97], v[12:13], v[128:129], v[96:97]
	v_pk_fma_f32 v[98:99], v[14:15], v[130:131], v[98:99]
	v_lshlrev_b32_e32 v100, 16, v60
	v_and_b32_e32 v101, 0xffff0000, v60
	v_lshlrev_b32_e32 v102, 16, v61
	v_and_b32_e32 v103, 0xffff0000, v61
	v_lshlrev_b32_e32 v104, 16, v62
	v_and_b32_e32 v105, 0xffff0000, v62
	v_lshlrev_b32_e32 v106, 16, v63
	v_and_b32_e32 v107, 0xffff0000, v63
	v_lshlrev_b32_e32 v124, 16, v72
	v_and_b32_e32 v125, 0xffff0000, v72
	v_lshlrev_b32_e32 v126, 16, v73
	v_and_b32_e32 v127, 0xffff0000, v73
	v_lshlrev_b32_e32 v128, 16, v74
	v_and_b32_e32 v129, 0xffff0000, v74
	v_lshlrev_b32_e32 v130, 16, v75
	v_and_b32_e32 v131, 0xffff0000, v75
	v_pk_add_f32 v[124:125], v[124:125], v[100:101] neg_lo:[0,1] neg_hi:[0,1]
	v_pk_add_f32 v[126:127], v[126:127], v[102:103] neg_lo:[0,1] neg_hi:[0,1]
	v_pk_add_f32 v[128:129], v[128:129], v[104:105] neg_lo:[0,1] neg_hi:[0,1]
	v_pk_add_f32 v[130:131], v[130:131], v[106:107] neg_lo:[0,1] neg_hi:[0,1]
	v_pk_fma_f32 v[100:101], v[16:17], v[124:125], v[100:101]
	v_pk_fma_f32 v[102:103], v[18:19], v[126:127], v[102:103]
	v_pk_fma_f32 v[104:105], v[20:21], v[128:129], v[104:105]
	v_pk_fma_f32 v[106:107], v[22:23], v[130:131], v[106:107]
	v_lshlrev_b32_e32 v108, 16, v80
	v_and_b32_e32 v109, 0xffff0000, v80
	v_lshlrev_b32_e32 v110, 16, v81
	v_and_b32_e32 v111, 0xffff0000, v81
	v_lshlrev_b32_e32 v112, 16, v82
	v_and_b32_e32 v113, 0xffff0000, v82
	v_lshlrev_b32_e32 v114, 16, v83
	v_and_b32_e32 v115, 0xffff0000, v83
	v_lshlrev_b32_e32 v116, 16, v76
	v_and_b32_e32 v117, 0xffff0000, v76
	v_lshlrev_b32_e32 v118, 16, v77
	v_and_b32_e32 v119, 0xffff0000, v77
	v_lshlrev_b32_e32 v120, 16, v78
	v_and_b32_e32 v121, 0xffff0000, v78
	v_lshlrev_b32_e32 v122, 16, v79
	v_and_b32_e32 v123, 0xffff0000, v79
	v_pk_mul_f32 v[132:133], v[92:93], v[24:25]
	v_pk_mul_f32 v[134:135], v[94:95], v[26:27]
	v_pk_mul_f32 v[136:137], v[96:97], v[28:29]
	v_pk_mul_f32 v[138:139], v[98:99], v[30:31]
	v_pk_add_f32 v[124:125], v[108:109], -1.0 op_sel_hi:[1,0]
	v_pk_add_f32 v[126:127], v[110:111], -1.0 op_sel_hi:[1,0]
	v_pk_add_f32 v[128:129], v[112:113], -1.0 op_sel_hi:[1,0]
	v_pk_add_f32 v[130:131], v[114:115], -1.0 op_sel_hi:[1,0]
	v_pk_fma_f32 v[124:125], v[32:33], v[124:125], 1.0 op_sel_hi:[1,1,0]
	v_pk_fma_f32 v[126:127], v[34:35], v[126:127], 1.0 op_sel_hi:[1,1,0]
	v_pk_fma_f32 v[128:129], v[36:37], v[128:129], 1.0 op_sel_hi:[1,1,0]
	v_pk_fma_f32 v[130:131], v[38:39], v[130:131], 1.0 op_sel_hi:[1,1,0]
	v_pk_mul_f32 v[140:141], v[124:125], v[92:93]
	v_pk_mul_f32 v[142:143], v[126:127], v[94:95]
	v_pk_mul_f32 v[144:145], v[128:129], v[96:97]
	v_pk_mul_f32 v[146:147], v[130:131], v[98:99]
	v_pk_mul_f32 v[148:149], v[84:85], v[140:141]
	v_pk_mul_f32 v[150:151], v[86:87], v[142:143]
	v_pk_mul_f32 v[152:153], v[88:89], v[144:145]
	v_pk_mul_f32 v[154:155], v[90:91], v[146:147]
	v_pk_mul_f32 v[156:157], v[132:133], v[108:109]
	v_pk_mul_f32 v[158:159], v[134:135], v[110:111]
	v_pk_mul_f32 v[160:161], v[136:137], v[112:113]
	v_pk_mul_f32 v[162:163], v[138:139], v[114:115]
	v_pk_mul_f32 v[124:125], v[148:149], v[40:41]
	v_pk_mul_f32 v[126:127], v[150:151], v[42:43]
	v_pk_mul_f32 v[128:129], v[152:153], v[44:45]
	v_pk_mul_f32 v[130:131], v[154:155], v[46:47]
	v_pk_add_f32 v[124:125], v[124:125], v[126:127]
	v_pk_add_f32 v[128:129], v[128:129], v[130:131]
	v_pk_add_f32 v[124:125], v[124:125], v[128:129]
	v_add_f32_e32 v173, v124, v125
	v_pk_mul_f32 v[124:125], v[156:157], v[84:85]
	v_pk_mul_f32 v[126:127], v[158:159], v[86:87]
	v_pk_mul_f32 v[128:129], v[160:161], v[88:89]
	v_pk_mul_f32 v[130:131], v[162:163], v[90:91]
	v_pk_add_f32 v[124:125], v[124:125], v[126:127]
	v_pk_add_f32 v[128:129], v[128:129], v[130:131]
	v_pk_add_f32 v[124:125], v[124:125], v[128:129]
	v_add_f32_e32 v174, v124, v125
	v_pk_mul_f32 v[124:125], v[132:133], v[132:133]
	v_pk_mul_f32 v[126:127], v[134:135], v[134:135]
	v_pk_mul_f32 v[128:129], v[136:137], v[136:137]
	v_pk_mul_f32 v[130:131], v[138:139], v[138:139]
	v_pk_add_f32 v[124:125], v[124:125], v[126:127]
	v_pk_add_f32 v[128:129], v[128:129], v[130:131]
	v_pk_add_f32 v[124:125], v[124:125], v[128:129]
	v_add_f32_e32 v172, v124, v125
	v_pk_add_f32 v[148:149], v[148:149], v[150:151]
	v_pk_add_f32 v[152:153], v[152:153], v[154:155]
	v_pk_add_f32 v[148:149], v[148:149], v[152:153]
	v_add_f32_e32 v175, v148, v149
	v_pk_mul_f32 v[116:117], v[116:117], v[48:49]
	v_pk_mul_f32 v[118:119], v[118:119], v[48:49]
	v_pk_mul_f32 v[120:121], v[120:121], v[48:49]
	v_pk_mul_f32 v[122:123], v[122:123], v[48:49]
	v_add_f32_dpp v172, v172, v172 quad_perm:[1,0,3,2] row_mask:0xf bank_mask:0xf bound_ctrl:1
	v_add_f32_dpp v173, v173, v173 quad_perm:[1,0,3,2] row_mask:0xf bank_mask:0xf bound_ctrl:1
	v_add_f32_dpp v174, v174, v174 quad_perm:[1,0,3,2] row_mask:0xf bank_mask:0xf bound_ctrl:1
	v_add_f32_dpp v175, v175, v175 quad_perm:[1,0,3,2] row_mask:0xf bank_mask:0xf bound_ctrl:1
	v_add_f32_dpp v172, v172, v172 quad_perm:[2,3,0,1] row_mask:0xf bank_mask:0xf bound_ctrl:1
	v_add_f32_dpp v173, v173, v173 quad_perm:[2,3,0,1] row_mask:0xf bank_mask:0xf bound_ctrl:1
	v_add_f32_dpp v174, v174, v174 quad_perm:[2,3,0,1] row_mask:0xf bank_mask:0xf bound_ctrl:1
	v_add_f32_dpp v175, v175, v175 quad_perm:[2,3,0,1] row_mask:0xf bank_mask:0xf bound_ctrl:1
	v_add_f32_dpp v172, v172, v172 row_half_mirror row_mask:0xf bank_mask:0xf bound_ctrl:1
	v_add_f32_dpp v173, v173, v173 row_half_mirror row_mask:0xf bank_mask:0xf bound_ctrl:1
	v_add_f32_dpp v174, v174, v174 row_half_mirror row_mask:0xf bank_mask:0xf bound_ctrl:1
	v_add_f32_dpp v175, v175, v175 row_half_mirror row_mask:0xf bank_mask:0xf bound_ctrl:1
	v_exp_f32_e32 v116, v116
	v_exp_f32_e32 v117, v117
	v_exp_f32_e32 v118, v118
	v_exp_f32_e32 v119, v119
	v_exp_f32_e32 v120, v120
	v_exp_f32_e32 v121, v121
	v_exp_f32_e32 v122, v122
	v_exp_f32_e32 v123, v123
	v_rsq_f32_e32 v176, v172
	v_pk_mul_f32 v[148:149], v[116:117], v[84:85]
	v_pk_mul_f32 v[150:151], v[118:119], v[86:87]
	v_pk_mul_f32 v[152:153], v[120:121], v[88:89]
	v_pk_mul_f32 v[154:155], v[122:123], v[90:91]
	v_min_f32_e32 v176, 0x5368d4a5, v176
	v_mul_f32_e32 v174, v174, v176
	v_pk_mul_f32 v[164:165], v[132:133], v[176:177] op_sel_hi:[1,0] neg_lo:[1,0] neg_hi:[1,0]
	v_pk_mul_f32 v[166:167], v[134:135], v[176:177] op_sel_hi:[1,0] neg_lo:[1,0] neg_hi:[1,0]
	v_pk_mul_f32 v[168:169], v[136:137], v[176:177] op_sel_hi:[1,0] neg_lo:[1,0] neg_hi:[1,0]
	v_pk_mul_f32 v[170:171], v[138:139], v[176:177] op_sel_hi:[1,0] neg_lo:[1,0] neg_hi:[1,0]
	v_pk_mul_f32 v[156:157], v[156:157], v[176:177] op_sel_hi:[1,0]
	v_pk_mul_f32 v[158:159], v[158:159], v[176:177] op_sel_hi:[1,0]
	v_pk_mul_f32 v[160:161], v[160:161], v[176:177] op_sel_hi:[1,0]
	v_pk_mul_f32 v[162:163], v[162:163], v[176:177] op_sel_hi:[1,0]
	s_mul_i32 s14, s13, 0xc000
	v_add_u32_e32 v198, s14, v194
	ds_write_b128 v198, v[148:151] offset:0
	ds_write_b128 v198, v[152:155] offset:128
	ds_write_b128 v198, v[116:119] offset:256
	ds_write_b128 v198, v[120:123] offset:384
	ds_write_b128 v198, v[140:143] offset:512
	ds_write_b128 v198, v[144:147] offset:640
	ds_write_b128 v198, v[164:167] offset:768
	ds_write_b128 v198, v[168:171] offset:896
	ds_write_b128 v198, v[156:159] offset:1024
	ds_write_b128 v198, v[160:163] offset:1152
	ds_write_b128 v198, v[100:103] offset:1280
	ds_write_b128 v198, v[104:107] offset:1408
	s_lshl_b32 s14, s13, 7
	v_add_u32_e32 v199, s14, v196
	s_lshl_b32 s14, s13, 8
	v_add_u32_e32 v198, s14, v197
	ds_write_b32 v199, v173
	ds_write_b64 v198, v[174:175]
	s_mov_b64 s[0:1], 0x34000
	v_lshl_add_u64 v[178:179], v[178:179], 0, s[0:1]
	v_lshl_add_u64 v[180:181], v[180:181], 0, s[0:1]
	v_lshl_add_u64 v[182:183], v[182:183], 0, s[0:1]
	s_mov_b64 s[0:1], 0x10000
	v_lshl_add_u64 v[186:187], v[186:187], 0, s[0:1]
	v_lshl_add_u64 v[188:189], v[188:189], 0, s[0:1]
	global_load_dwordx2 v[52:53], v[178:179], off
	global_load_dwordx2 v[54:55], v[178:179], off offset:64
	global_load_dwordx2 v[56:57], v[178:179], off offset:2048
	global_load_dwordx2 v[58:59], v[178:179], off offset:2112
	global_load_dwordx2 v[60:61], v[180:181], off
	global_load_dwordx2 v[62:63], v[180:181], off offset:64
	global_load_dwordx2 v[64:65], v[182:183], off offset:-2560
	global_load_dwordx2 v[66:67], v[182:183], off offset:-2496
	global_load_dwordx2 v[68:69], v[182:183], off offset:-512
	global_load_dwordx2 v[70:71], v[182:183], off offset:-448
	global_load_dwordx2 v[72:73], v[178:179], off offset:-2560
	global_load_dwordx2 v[74:75], v[178:179], off offset:-2496
	global_load_dwordx2 v[76:77], v[186:187], off
	global_load_dwordx2 v[78:79], v[186:187], off offset:64
	global_load_dwordx2 v[80:81], v[188:189], off
	global_load_dwordx2 v[82:83], v[188:189], off offset:64
	s_waitcnt lgkmcnt(0)
	s_barrier
	s_waitcnt vmcnt(0)
	s_mov_b32 s12, 0

.Lh_nopost:
	s_cmp_lt_u32 s12, 64
	s_cbranch_scc0 .Lh_nobuild
	s_add_i32 s13, s12, 1
	s_and_b32 s13, s13, 1
	s_waitcnt vmcnt(1)
	v_lshlrev_b32_e32 v84, 16, v52
	v_and_b32_e32 v85, 0xffff0000, v52
	v_lshlrev_b32_e32 v86, 16, v53
	v_and_b32_e32 v87, 0xffff0000, v53
	v_lshlrev_b32_e32 v88, 16, v54
	v_and_b32_e32 v89, 0xffff0000, v54
	v_lshlrev_b32_e32 v90, 16, v55
	v_and_b32_e32 v91, 0xffff0000, v55
	v_lshlrev_b32_e32 v124, 16, v64
	v_and_b32_e32 v125, 0xffff0000, v64
	v_lshlrev_b32_e32 v126, 16, v65
	v_and_b32_e32 v127, 0xffff0000, v65
	v_lshlrev_b32_e32 v128, 16, v66
	v_and_b32_e32 v129, 0xffff0000, v66
	v_lshlrev_b32_e32 v130, 16, v67
	v_and_b32_e32 v131, 0xffff0000, v67
	v_pk_add_f32 v[124:125], v[124:125], v[84:85] neg_lo:[0,1] neg_hi:[0,1]
	v_pk_add_f32 v[126:127], v[126:127], v[86:87] neg_lo:[0,1] neg_hi:[0,1]
	v_pk_add_f32 v[128:129], v[128:129], v[88:89] neg_lo:[0,1] neg_hi:[0,1]
	v_pk_add_f32 v[130:131], v[130:131], v[90:91] neg_lo:[0,1] neg_hi:[0,1]
	v_pk_fma_f32 v[84:85], v[0:1], v[124:125], v[84:85]
	v_pk_fma_f32 v[86:87], v[2:3], v[126:127], v[86:87]
	v_pk_fma_f32 v[88:89], v[4:5], v[128:129], v[88:89]
	v_pk_fma_f32 v[90:91], v[6:7], v[130:131], v[90:91]
	v_lshlrev_b32_e32 v92, 16, v56
	v_and_b32_e32 v93, 0xffff0000, v56
	v_lshlrev_b32_e32 v94, 16, v57
	v_and_b32_e32 v95, 0xffff0000, v57
	v_lshlrev_b32_e32 v96, 16, v58
	v_and_b32_e32 v97, 0xffff0000, v58
	v_lshlrev_b32_e32 v98, 16, v59
	v_and_b32_e32 v99, 0xffff0000, v59
	v_lshlrev_b32_e32 v124, 16, v68
	v_and_b32_e32 v125, 0xffff0000, v68
	v_lshlrev_b32_e32 v126, 16, v69
	v_and_b32_e32 v127, 0xffff0000, v69
	v_lshlrev_b32_e32 v128, 16, v70
	v_and_b32_e32 v129, 0xffff0000, v70
	v_lshlrev_b32_e32 v130, 16, v71
	v_and_b32_e32 v131, 0xffff0000, v71
	v_pk_add_f32 v[124:125], v[124:125], v[92:93] neg_lo:[0,1] neg_hi:[0,1]
	v_pk_add_f32 v[126:127], v[126:127], v[94:95] neg_lo:[0,1] neg_hi:[0,1]
	v_pk_add_f32 v[128:129], v[128:129], v[96:97] neg_lo:[0,1] neg_hi:[0,1]
	v_pk_add_f32 v[130:131], v[130:131], v[98:99] neg_lo:[0,1] neg_hi:[0,1]
	v_pk_fma_f32 v[92:93], v[8:9], v[124:125], v[92:93]
	v_pk_fma_f32 v[94:95], v[10:11], v[126:127], v[94:95]
	v_pk_fma_f32 v[96:97], v[12:13], v[128:129], v[96:97]
	v_pk_fma_f32 v[98:99], v[14:15], v[130:131], v[98:99]
	v_lshlrev_b32_e32 v100, 16, v60
	v_and_b32_e32 v101, 0xffff0000, v60
	v_lshlrev_b32_e32 v102, 16, v61
	v_and_b32_e32 v103, 0xffff0000, v61
	v_lshlrev_b32_e32 v104, 16, v62
	v_and_b32_e32 v105, 0xffff0000, v62
	v_lshlrev_b32_e32 v106, 16, v63
	v_and_b32_e32 v107, 0xffff0000, v63
	v_lshlrev_b32_e32 v124, 16, v72
	v_and_b32_e32 v125, 0xffff0000, v72
	v_lshlrev_b32_e32 v126, 16, v73
	v_and_b32_e32 v127, 0xffff0000, v73
	v_lshlrev_b32_e32 v128, 16, v74
	v_and_b32_e32 v129, 0xffff0000, v74
	v_lshlrev_b32_e32 v130, 16, v75
	v_and_b32_e32 v131, 0xffff0000, v75
	v_pk_add_f32 v[124:125], v[124:125], v[100:101] neg_lo:[0,1] neg_hi:[0,1]
	v_pk_add_f32 v[126:127], v[126:127], v[102:103] neg_lo:[0,1] neg_hi:[0,1]
	v_pk_add_f32 v[128:129], v[128:129], v[104:105] neg_lo:[0,1] neg_hi:[0,1]
	v_pk_add_f32 v[130:131], v[130:131], v[106:107] neg_lo:[0,1] neg_hi:[0,1]
	v_pk_fma_f32 v[100:101], v[16:17], v[124:125], v[100:101]
	v_pk_fma_f32 v[102:103], v[18:19], v[126:127], v[102:103]
	v_pk_fma_f32 v[104:105], v[20:21], v[128:129], v[104:105]
	v_pk_fma_f32 v[106:107], v[22:23], v[130:131], v[106:107]
	v_lshlrev_b32_e32 v108, 16, v80
	v_and_b32_e32 v109, 0xffff0000, v80
	v_lshlrev_b32_e32 v110, 16, v81
	v_and_b32_e32 v111, 0xffff0000, v81
	v_lshlrev_b32_e32 v112, 16, v82
	v_and_b32_e32 v113, 0xffff0000, v82
	v_lshlrev_b32_e32 v114, 16, v83
	v_and_b32_e32 v115, 0xffff0000, v83
	v_lshlrev_b32_e32 v116, 16, v76
	v_and_b32_e32 v117, 0xffff0000, v76
	v_lshlrev_b32_e32 v118, 16, v77
	v_and_b32_e32 v119, 0xffff0000, v77
	v_lshlrev_b32_e32 v120, 16, v78
	v_and_b32_e32 v121, 0xffff0000, v78
	v_lshlrev_b32_e32 v122, 16, v79
	v_and_b32_e32 v123, 0xffff0000, v79
	v_pk_mul_f32 v[132:133], v[92:93], v[24:25]
	v_pk_mul_f32 v[134:135], v[94:95], v[26:27]
	v_pk_mul_f32 v[136:137], v[96:97], v[28:29]
	v_pk_mul_f32 v[138:139], v[98:99], v[30:31]
	v_pk_add_f32 v[124:125], v[108:109], -1.0 op_sel_hi:[1,0]
	v_pk_add_f32 v[126:127], v[110:111], -1.0 op_sel_hi:[1,0]
	v_pk_add_f32 v[128:129], v[112:113], -1.0 op_sel_hi:[1,0]
	v_pk_add_f32 v[130:131], v[114:115], -1.0 op_sel_hi:[1,0]
	v_pk_fma_f32 v[124:125], v[32:33], v[124:125], 1.0 op_sel_hi:[1,1,0]
	v_pk_fma_f32 v[126:127], v[34:35], v[126:127], 1.0 op_sel_hi:[1,1,0]
	v_pk_fma_f32 v[128:129], v[36:37], v[128:129], 1.0 op_sel_hi:[1,1,0]
	v_pk_fma_f32 v[130:131], v[38:39], v[130:131], 1.0 op_sel_hi:[1,1,0]
	v_pk_mul_f32 v[140:141], v[124:125], v[92:93]
	v_pk_mul_f32 v[142:143], v[126:127], v[94:95]
	v_pk_mul_f32 v[144:145], v[128:129], v[96:97]
	v_pk_mul_f32 v[146:147], v[130:131], v[98:99]
	v_pk_mul_f32 v[148:149], v[84:85], v[140:141]
	v_pk_mul_f32 v[150:151], v[86:87], v[142:143]
	v_pk_mul_f32 v[152:153], v[88:89], v[144:145]
	v_pk_mul_f32 v[154:155], v[90:91], v[146:147]
	v_pk_mul_f32 v[156:157], v[132:133], v[108:109]
	v_pk_mul_f32 v[158:159], v[134:135], v[110:111]
	v_pk_mul_f32 v[160:161], v[136:137], v[112:113]
	v_pk_mul_f32 v[162:163], v[138:139], v[114:115]
	v_pk_mul_f32 v[124:125], v[148:149], v[40:41]
	v_pk_mul_f32 v[126:127], v[150:151], v[42:43]
	v_pk_mul_f32 v[128:129], v[152:153], v[44:45]
	v_pk_mul_f32 v[130:131], v[154:155], v[46:47]
	v_pk_add_f32 v[124:125], v[124:125], v[126:127]
	v_pk_add_f32 v[128:129], v[128:129], v[130:131]
	v_pk_add_f32 v[124:125], v[124:125], v[128:129]
	v_add_f32_e32 v173, v124, v125
	v_pk_mul_f32 v[124:125], v[156:157], v[84:85]
	v_pk_mul_f32 v[126:127], v[158:159], v[86:87]
	v_pk_mul_f32 v[128:129], v[160:161], v[88:89]
	v_pk_mul_f32 v[130:131], v[162:163], v[90:91]
	v_pk_add_f32 v[124:125], v[124:125], v[126:127]
	v_pk_add_f32 v[128:129], v[128:129], v[130:131]
	v_pk_add_f32 v[124:125], v[124:125], v[128:129]
	v_add_f32_e32 v174, v124, v125
	v_pk_mul_f32 v[124:125], v[132:133], v[132:133]
	v_pk_mul_f32 v[126:127], v[134:135], v[134:135]
	v_pk_mul_f32 v[128:129], v[136:137], v[136:137]
	v_pk_mul_f32 v[130:131], v[138:139], v[138:139]
	v_pk_add_f32 v[124:125], v[124:125], v[126:127]
	v_pk_add_f32 v[128:129], v[128:129], v[130:131]
	v_pk_add_f32 v[124:125], v[124:125], v[128:129]
	v_add_f32_e32 v172, v124, v125
	v_pk_add_f32 v[148:149], v[148:149], v[150:151]
	v_pk_add_f32 v[152:153], v[152:153], v[154:155]
	v_pk_add_f32 v[148:149], v[148:149], v[152:153]
	v_add_f32_e32 v175, v148, v149
	v_pk_mul_f32 v[116:117], v[116:117], v[48:49]
	v_pk_mul_f32 v[118:119], v[118:119], v[48:49]
	v_pk_mul_f32 v[120:121], v[120:121], v[48:49]
	v_pk_mul_f32 v[122:123], v[122:123], v[48:49]
	v_add_f32_dpp v172, v172, v172 quad_perm:[1,0,3,2] row_mask:0xf bank_mask:0xf bound_ctrl:1
	v_add_f32_dpp v173, v173, v173 quad_perm:[1,0,3,2] row_mask:0xf bank_mask:0xf bound_ctrl:1
	v_add_f32_dpp v174, v174, v174 quad_perm:[1,0,3,2] row_mask:0xf bank_mask:0xf bound_ctrl:1
	v_add_f32_dpp v175, v175, v175 quad_perm:[1,0,3,2] row_mask:0xf bank_mask:0xf bound_ctrl:1
	v_add_f32_dpp v172, v172, v172 quad_perm:[2,3,0,1] row_mask:0xf bank_mask:0xf bound_ctrl:1
	v_add_f32_dpp v173, v173, v173 quad_perm:[2,3,0,1] row_mask:0xf bank_mask:0xf bound_ctrl:1
	v_add_f32_dpp v174, v174, v174 quad_perm:[2,3,0,1] row_mask:0xf bank_mask:0xf bound_ctrl:1
	v_add_f32_dpp v175, v175, v175 quad_perm:[2,3,0,1] row_mask:0xf bank_mask:0xf bound_ctrl:1
	v_add_f32_dpp v172, v172, v172 row_half_mirror row_mask:0xf bank_mask:0xf bound_ctrl:1
	v_add_f32_dpp v173, v173, v173 row_half_mirror row_mask:0xf bank_mask:0xf bound_ctrl:1
	v_add_f32_dpp v174, v174, v174 row_half_mirror row_mask:0xf bank_mask:0xf bound_ctrl:1
	v_add_f32_dpp v175, v175, v175 row_half_mirror row_mask:0xf bank_mask:0xf bound_ctrl:1
	v_exp_f32_e32 v116, v116
	v_exp_f32_e32 v117, v117
	v_exp_f32_e32 v118, v118
	v_exp_f32_e32 v119, v119
	v_exp_f32_e32 v120, v120
	v_exp_f32_e32 v121, v121
	v_exp_f32_e32 v122, v122
	v_exp_f32_e32 v123, v123
	v_rsq_f32_e32 v176, v172
	v_pk_mul_f32 v[148:149], v[116:117], v[84:85]
	v_pk_mul_f32 v[150:151], v[118:119], v[86:87]
	v_pk_mul_f32 v[152:153], v[120:121], v[88:89]
	v_pk_mul_f32 v[154:155], v[122:123], v[90:91]
	v_min_f32_e32 v176, 0x5368d4a5, v176
	v_mul_f32_e32 v174, v174, v176
	v_pk_mul_f32 v[164:165], v[132:133], v[176:177] op_sel_hi:[1,0] neg_lo:[1,0] neg_hi:[1,0]
	v_pk_mul_f32 v[166:167], v[134:135], v[176:177] op_sel_hi:[1,0] neg_lo:[1,0] neg_hi:[1,0]
	v_pk_mul_f32 v[168:169], v[136:137], v[176:177] op_sel_hi:[1,0] neg_lo:[1,0] neg_hi:[1,0]
	v_pk_mul_f32 v[170:171], v[138:139], v[176:177] op_sel_hi:[1,0] neg_lo:[1,0] neg_hi:[1,0]
	v_pk_mul_f32 v[156:157], v[156:157], v[176:177] op_sel_hi:[1,0]
	v_pk_mul_f32 v[158:159], v[158:159], v[176:177] op_sel_hi:[1,0]
	v_pk_mul_f32 v[160:161], v[160:161], v[176:177] op_sel_hi:[1,0]
	v_pk_mul_f32 v[162:163], v[162:163], v[176:177] op_sel_hi:[1,0]
	s_mul_i32 s14, s13, 0xc000
	v_add_u32_e32 v198, s14, v194
	ds_write_b128 v198, v[148:151] offset:0
	ds_write_b128 v198, v[152:155] offset:128
	ds_write_b128 v198, v[116:119] offset:256
	ds_write_b128 v198, v[120:123] offset:384
	ds_write_b128 v198, v[140:143] offset:512
	ds_write_b128 v198, v[144:147] offset:640
	ds_write_b128 v198, v[164:167] offset:768
	ds_write_b128 v198, v[168:171] offset:896
	ds_write_b128 v198, v[156:159] offset:1024
	ds_write_b128 v198, v[160:163] offset:1152
	ds_write_b128 v198, v[100:103] offset:1280
	ds_write_b128 v198, v[104:107] offset:1408
	s_lshl_b32 s14, s13, 7
	v_add_u32_e32 v199, s14, v196
	s_lshl_b32 s14, s13, 8
	v_add_u32_e32 v198, s14, v197
	ds_write_b32 v199, v173
	ds_write_b64 v198, v[174:175]
	s_cmp_eq_u32 s34, 0
	s_cbranch_scc1 .Lcv_noproc
	s_cmp_eq_u32 s35, 0
	s_cbranch_scc1 .Lcv_noscale
	v_mul_f32_e32 v242, v242, v223
	v_mul_f32_e32 v243, v243, v223
	v_mul_f32_e32 v244, v244, v223
	v_mul_f32_e32 v245, v245, v223
	v_mul_f32_e32 v246, v246, v223
	v_mul_f32_e32 v247, v247, v223
	v_mul_f32_e32 v248, v248, v223
	v_mul_f32_e32 v249, v249, v223
	v_mul_f32_e32 v236, v236, v223
	v_mul_f32_e32 v237, v237, v223
	v_mul_f32_e32 v238, v238, v223
	v_mul_f32_e32 v239, v239, v223
	v_mul_f32_e32 v224, v224, v223
	v_mul_f32_e32 v225, v225, v223
	v_mul_f32_e32 v226, v226, v223
	v_mul_f32_e32 v227, v227, v223
.Lcv_noscale:
	s_nop 1
	v_mov_b32_dpp v84, v242 quad_perm:[1,0,3,2] row_mask:0xf bank_mask:0xf
	v_mov_b32_dpp v85, v243 quad_perm:[1,0,3,2] row_mask:0xf bank_mask:0xf
	v_mov_b32_dpp v89, v244 quad_perm:[1,0,3,2] row_mask:0xf bank_mask:0xf
	v_mov_b32_dpp v90, v245 quad_perm:[1,0,3,2] row_mask:0xf bank_mask:0xf
	v_mov_b32_dpp v94, v246 quad_perm:[1,0,3,2] row_mask:0xf bank_mask:0xf
	v_mov_b32_dpp v95, v247 quad_perm:[1,0,3,2] row_mask:0xf bank_mask:0xf
	v_mov_b32_dpp v99, v248 quad_perm:[1,0,3,2] row_mask:0xf bank_mask:0xf
	v_mov_b32_dpp v100, v249 quad_perm:[1,0,3,2] row_mask:0xf bank_mask:0xf
	v_mov_b32_dpp v104, v236 quad_perm:[1,0,3,2] row_mask:0xf bank_mask:0xf
	v_mov_b32_dpp v105, v237 quad_perm:[1,0,3,2] row_mask:0xf bank_mask:0xf
	v_mov_b32_dpp v109, v238 quad_perm:[1,0,3,2] row_mask:0xf bank_mask:0xf
	v_mov_b32_dpp v110, v239 quad_perm:[1,0,3,2] row_mask:0xf bank_mask:0xf
	v_mov_b32_dpp v114, v224 quad_perm:[1,0,3,2] row_mask:0xf bank_mask:0xf
	v_mov_b32_dpp v115, v225 quad_perm:[1,0,3,2] row_mask:0xf bank_mask:0xf
	v_mov_b32_dpp v119, v226 quad_perm:[1,0,3,2] row_mask:0xf bank_mask:0xf
	v_mov_b32_dpp v120, v227 quad_perm:[1,0,3,2] row_mask:0xf bank_mask:0xf
	v_cndmask_b32_e64 v86, v85, v242, s[62:63]
	v_cndmask_b32_e64 v87, v243, v84, s[62:63]
	v_cvt_pk_bf16_f32 v88, v86, v87
	v_cndmask_b32_e64 v91, v90, v244, s[62:63]
	v_cndmask_b32_e64 v92, v245, v89, s[62:63]
	v_cvt_pk_bf16_f32 v93, v91, v92
	v_cndmask_b32_e64 v96, v95, v246, s[62:63]
	v_cndmask_b32_e64 v97, v247, v94, s[62:63]
	v_cvt_pk_bf16_f32 v98, v96, v97
	v_cndmask_b32_e64 v101, v100, v248, s[62:63]
	v_cndmask_b32_e64 v102, v249, v99, s[62:63]
	v_cvt_pk_bf16_f32 v103, v101, v102
	v_cndmask_b32_e64 v106, v105, v236, s[62:63]
	v_cndmask_b32_e64 v107, v237, v104, s[62:63]
	v_cvt_pk_bf16_f32 v108, v106, v107
	v_cndmask_b32_e64 v111, v110, v238, s[62:63]
	v_cndmask_b32_e64 v112, v239, v109, s[62:63]
	v_cvt_pk_bf16_f32 v113, v111, v112
	v_cndmask_b32_e64 v116, v115, v224, s[62:63]
	v_cndmask_b32_e64 v117, v225, v114, s[62:63]
	v_cvt_pk_bf16_f32 v118, v116, v117
	v_cndmask_b32_e64 v121, v120, v226, s[62:63]
	v_cndmask_b32_e64 v122, v227, v119, s[62:63]
	v_cvt_pk_bf16_f32 v123, v121, v122
	global_store_dword v232, v88, s[50:51]
	s_add_u32 s50, s50, s52
	s_addc_u32 s51, s51, 0
	global_store_dword v232, v93, s[50:51]
	s_add_u32 s50, s50, s52
	s_addc_u32 s51, s51, 0
	global_store_dword v232, v98, s[50:51]
	s_add_u32 s50, s50, s52
	s_addc_u32 s51, s51, 0
	global_store_dword v232, v103, s[50:51]
	s_add_u32 s50, s50, s52
	s_addc_u32 s51, s51, 0
	global_store_dword v232, v108, s[50:51]
	s_add_u32 s50, s50, s52
	s_addc_u32 s51, s51, 0
	global_store_dword v232, v113, s[50:51]
	s_add_u32 s50, s50, s52
	s_addc_u32 s51, s51, 0
	global_store_dword v232, v118, s[50:51]
	s_add_u32 s50, s50, s52
	s_addc_u32 s51, s51, 0
	global_store_dword v232, v123, s[50:51]
.Lcv_noproc:
	s_mov_b32 s34, 0
	s_lshl_b32 s54, s12, 10
	s_add_i32 s54, s54, s53
	s_mov_b32 s55, 0x2500
	s_cmp_eq_u32 s30, 0
	s_cselect_b32 s55, 0x4600, s55
	s_cmp_lt_u32 s54, s55
	s_cbranch_scc0 .Lcv_noitem
	s_lshl_b32 s61, s30, 12
	s_cmp_lt_u32 s54, 0x400
	s_cbranch_scc0 .Lcv_j1
	v_readlane_b32 s58, v255, 17
	v_readlane_b32 s59, v255, 18
	s_lshl_b32 s4, s30, 22
	s_mov_b32 s60, 0x2100000
	s_mov_b32 s57, 0
	s_branch .Lcv_jsel
.Lcv_j1:
	s_cmp_lt_u32 s54, 0x1a00
	s_cbranch_scc0 .Lcv_j2
	s_sub_u32 s54, s54, 0x400
	s_mov_b64 s[58:59], s[22:23]
	s_mul_i32 s4, s30, 0x1600000
	s_add_u32 s6, s20, s61
	s_addc_u32 s7, s21, 0
	s_mov_b32 s60, 0x2300000
	s_mov_b32 s57, 1
	s_branch .Lcv_jsel
.Lcv_j2:
	s_cmp_lt_u32 s54, 0x2500
	s_cbranch_scc0 .Lcv_j3
	s_sub_u32 s54, s54, 0x1a00
	s_mov_b64 s[58:59], s[24:25]
	s_mul_i32 s4, s30, 0xb00000
	s_mov_b32 s60, 0x2e00000
	s_mov_b32 s57, 2
	s_branch .Lcv_jsel
.Lcv_j3:
	s_cmp_lt_u32 s54, 0x3b00
	s_cbranch_scc0 .Lcv_j4
	s_sub_u32 s54, s54, 0x2500
	v_readlane_b32 s58, v254, 49
	v_readlane_b32 s59, v254, 50
	v_readlane_b32 s6, v254, 47
	v_readlane_b32 s7, v254, 48
	s_mov_b32 s4, 0x1600000
	s_mov_b32 s60, 0
	s_mov_b32 s57, 1
	s_nop 1
	s_add_u32 s6, s6, 0x1000
	s_addc_u32 s7, s7, 0
	s_branch .Lcv_jsel
.Lcv_j4:
	s_sub_u32 s54, s54, 0x3b00
	v_readlane_b32 s58, v254, 51
	v_readlane_b32 s59, v254, 52
	s_mov_b32 s4, 0xb00000
	s_mov_b32 s60, 0xb00000
	s_mov_b32 s57, 2
.Lcv_jsel:
	s_nop 1
	s_add_u32 s58, s58, s4
	s_addc_u32 s59, s59, 0
	s_cmp_eq_u32 s57, 1
	s_cbranch_scc1 .Lcv_shb
	s_and_b32 s55, s54, 63
	s_lshr_b32 s56, s54, 6
	s_lshl_b32 s0, s55, 4
	s_mov_b32 s1, 0x1000
	s_mov_b32 s5, 0xb00
	s_cmp_eq_u32 s57, 0
	s_cselect_b32 s5, 0x400, s5
	s_mov_b32 s35, 0
	s_branch .Lcv_shdone
.Lcv_shb:
	s_lshr_b32 s56, s54, 5
	s_mul_i32 s56, s56, 0xba2f
	s_lshr_b32 s56, s56, 19
	s_mul_i32 s55, s56, 0x160
	s_sub_u32 s55, s54, s55
	s_lshl_b32 s0, s55, 4
	s_lshr_b32 s1, s0, 8
	s_lshl_b32 s1, s1, 7
	s_and_b32 s5, s0, 0x7f
	s_add_i32 s1, s1, s5
	s_and_b32 s5, s0, 0x80
	s_cmp_lg_u32 s5, 0
	s_cselect_b32 s5, 0xb00, 0
	s_add_i32 s0, s1, s5
	s_mov_b32 s1, 0x5800
	s_mov_b32 s5, 0x400
	s_mov_b32 s35, 1
.Lcv_shdone:
	s_lshl_b32 s14, s56, 6
	s_mul_i32 s4, s14, s1
	s_lshl_b32 s0, s0, 2
	s_add_i32 s4, s4, s0
	s_add_u32 s58, s58, s4
	s_addc_u32 s59, s59, 0
	v_mul_u32_u24_e32 v84, s1, v231
	global_load_dwordx4 v[242:245], v84, s[58:59]
	global_load_dwordx4 v[246:249], v84, s[58:59] offset:16
	global_load_dwordx4 v[236:239], v84, s[58:59] offset:32
	global_load_dwordx4 v[224:227], v84, s[58:59] offset:48
	s_cmp_eq_u32 s35, 0
	s_cbranch_scc1 .Lcv_nosl
	s_lshl_b32 s4, s14, 2
	s_add_u32 s6, s6, s4
	s_addc_u32 s7, s7, 0
	global_load_dword v223, v250, s[6:7]
.Lcv_nosl:
	s_lshl_b32 s4, s55, 4
	s_mul_i32 s4, s4, s5
	s_add_i32 s4, s4, s14
	s_lshl_b32 s4, s4, 1
	s_add_u32 s50, s86, s60
	s_addc_u32 s51, s87, 0
	s_add_u32 s50, s50, s4
	s_addc_u32 s51, s51, 0
	s_lshl_b32 s52, s5, 2
	s_lshl_b32 s4, s5, 1
	v_mul_u32_u24_e32 v232, s4, v240
	v_add_u32_e32 v232, v232, v233
	s_mov_b32 s34, 1
